# peel first K-iteration with C=0 MFMAs instead of zeroing 128 acc VGPRs (SwiGLU+Resid loops)
# speedup vs baseline: 1.0075x; 1.0075x over previous
.LBB0_496:
	s_add_u32 s2, s2, 0x80
	s_addc_u32 s3, s3, 0
	s_add_u32 s40, s34, 0x100
	s_addc_u32 s41, s35, 0
	s_mov_b32 s34, 0
	s_waitcnt lgkmcnt(0)
	s_waitcnt vmcnt(0)
	s_add_i32 s86, s34, 2
	s_add_u32 s62, s2, 0x80
	s_addc_u32 s35, s3, 0
	s_add_i32 s63, 0, 0x10000
	s_cmp_eq_u32 s80, s34
	s_cselect_b32 s35, s17, s35
	s_cselect_b32 s34, s16, s62
	s_cselect_b32 s89, s25, s41
	s_cselect_b32 s88, s24, s40
	s_add_i32 s62, 0, 0x14000
	v_add_u32_e32 v140, s63, v201
	v_add_u32_e32 v180, s62, v201
	ds_read_b128 v[128:131], v140
	ds_read_b128 v[132:135], v140 offset:1024
	ds_read_b128 v[136:139], v140 offset:2048
	ds_read_b128 v[140:143], v140 offset:3072
	ds_read_b128 v[144:147], v180
	ds_read_b128 v[148:151], v180 offset:1024
	ds_read_b128 v[152:155], v180 offset:2048
	ds_read_b128 v[180:183], v180 offset:3072
	v_lshl_add_u64 v[192:193], s[2:3], 0, v[176:177]
	s_add_i32 m0, s48, 0xc000
	ds_read_b128 v[184:187], v202
	ds_read_b128 v[188:191], v202 offset:1024
	ds_read_b128 v[204:207], v202 offset:2048
	ds_read_b128 v[208:211], v202 offset:3072
	ds_read_b128 v[212:215], v202 offset:4096
	ds_read_b128 v[216:219], v202 offset:5120
	ds_read_b128 v[220:223], v202 offset:6144
	ds_read_b128 v[224:227], v202 offset:7168
	global_load_lds_dwordx4 v[192:193], off
	v_lshl_add_u64 v[192:193], s[2:3], 0, v[178:179]
	s_add_i32 m0, s48, 0xe000
	s_nop 0
	global_load_lds_dwordx4 v[192:193], off
	s_waitcnt vmcnt(8)
	s_waitcnt lgkmcnt(0)
	s_barrier
	s_setprio 1
	s_waitcnt lgkmcnt(0)
	v_mfma_f32_16x16x32_bf16 v[124:127], v[128:131], v[184:187], 0
	v_mfma_f32_16x16x32_bf16 v[120:123], v[136:139], v[184:187], 0
	v_mfma_f32_16x16x32_bf16 v[108:111], v[128:131], v[204:207], 0
	v_mfma_f32_16x16x32_bf16 v[104:107], v[136:139], v[204:207], 0
	v_mfma_f32_16x16x32_bf16 v[92:95], v[128:131], v[212:215], 0
	v_mfma_f32_16x16x32_bf16 v[88:91], v[136:139], v[212:215], 0
	v_mfma_f32_16x16x32_bf16 v[76:79], v[128:131], v[220:223], 0
	v_mfma_f32_16x16x32_bf16 v[72:75], v[136:139], v[220:223], 0
	v_mfma_f32_16x16x32_bf16 v[124:127], v[132:135], v[188:191], v[124:127]
	v_mfma_f32_16x16x32_bf16 v[120:123], v[140:143], v[188:191], v[120:123]
	v_mfma_f32_16x16x32_bf16 v[108:111], v[132:135], v[208:211], v[108:111]
	v_mfma_f32_16x16x32_bf16 v[104:107], v[140:143], v[208:211], v[104:107]
	v_mfma_f32_16x16x32_bf16 v[92:95], v[132:135], v[216:219], v[92:95]
	v_mfma_f32_16x16x32_bf16 v[88:91], v[140:143], v[216:219], v[88:91]
	v_mfma_f32_16x16x32_bf16 v[76:79], v[132:135], v[224:227], v[76:79]
	v_mfma_f32_16x16x32_bf16 v[72:75], v[140:143], v[224:227], v[72:75]
	s_setprio 0
	s_setprio 1
	v_mfma_f32_16x16x32_bf16 v[116:119], v[144:147], v[184:187], 0
	v_mfma_f32_16x16x32_bf16 v[112:115], v[152:155], v[184:187], 0
	v_mfma_f32_16x16x32_bf16 v[100:103], v[144:147], v[204:207], 0
	v_mfma_f32_16x16x32_bf16 v[96:99], v[152:155], v[204:207], 0
	v_mfma_f32_16x16x32_bf16 v[84:87], v[144:147], v[212:215], 0
	v_mfma_f32_16x16x32_bf16 v[80:83], v[152:155], v[212:215], 0
	v_mfma_f32_16x16x32_bf16 v[68:71], v[144:147], v[220:223], 0
	v_mfma_f32_16x16x32_bf16 v[64:67], v[152:155], v[220:223], 0
	v_mfma_f32_16x16x32_bf16 v[116:119], v[148:151], v[188:191], v[116:119]
	v_mfma_f32_16x16x32_bf16 v[112:115], v[180:183], v[188:191], v[112:115]
	v_mfma_f32_16x16x32_bf16 v[100:103], v[148:151], v[208:211], v[100:103]
	v_mfma_f32_16x16x32_bf16 v[96:99], v[180:183], v[208:211], v[96:99]
	v_mfma_f32_16x16x32_bf16 v[84:87], v[148:151], v[216:219], v[84:87]
	v_mfma_f32_16x16x32_bf16 v[80:83], v[180:183], v[216:219], v[80:83]
	v_mfma_f32_16x16x32_bf16 v[68:71], v[148:151], v[224:227], v[68:71]
	v_mfma_f32_16x16x32_bf16 v[64:67], v[180:183], v[224:227], v[64:67]
	s_setprio 0
	s_barrier
	s_add_i32 s63, s63, s47
	v_lshl_add_u64 v[192:193], s[88:89], 0, v[158:159]
	s_mov_b32 m0, s63
	ds_read_b128 v[184:187], v202 offset:16384
	ds_read_b128 v[188:191], v202 offset:17408
	ds_read_b128 v[204:207], v202 offset:18432
	ds_read_b128 v[208:211], v202 offset:19456
	ds_read_b128 v[212:215], v202 offset:20480
	ds_read_b128 v[216:219], v202 offset:21504
	ds_read_b128 v[220:223], v202 offset:22528
	ds_read_b128 v[224:227], v202 offset:23552
	global_load_lds_dwordx4 v[192:193], off
	s_add_i32 m0, s63, 0x2000
	v_lshl_add_u64 v[228:229], s[88:89], 0, v[168:169]
	s_add_u32 s88, s88, s8
	s_addc_u32 s89, s89, 0
	s_add_i32 s62, s62, s47
	global_load_lds_dwordx4 v[228:229], off
	v_lshl_add_u64 v[230:231], s[88:89], 0, v[158:159]
	s_mov_b32 m0, s62
	v_lshl_add_u64 v[232:233], s[88:89], 0, v[168:169]
	global_load_lds_dwordx4 v[230:231], off
	s_add_i32 m0, s62, 0x2000
	v_lshl_add_u64 v[234:235], s[34:35], 0, v[172:173]
	global_load_lds_dwordx4 v[232:233], off
	s_mov_b32 m0, s48
	v_lshl_add_u64 v[236:237], s[34:35], 0, v[170:171]
	global_load_lds_dwordx4 v[234:235], off
	s_mov_b32 m0, s49
	s_nop 0
	global_load_lds_dwordx4 v[236:237], off
	s_waitcnt vmcnt(8)
	s_waitcnt lgkmcnt(0)
	s_barrier
	s_setprio 1
	s_waitcnt lgkmcnt(0)
	v_mfma_f32_16x16x32_bf16 v[60:63], v[128:131], v[184:187], 0
	v_mfma_f32_16x16x32_bf16 v[56:59], v[136:139], v[184:187], 0
	v_mfma_f32_16x16x32_bf16 v[44:47], v[128:131], v[204:207], 0
	v_mfma_f32_16x16x32_bf16 v[40:43], v[136:139], v[204:207], 0
	v_mfma_f32_16x16x32_bf16 v[28:31], v[128:131], v[212:215], 0
	v_mfma_f32_16x16x32_bf16 v[24:27], v[136:139], v[212:215], 0
	v_mfma_f32_16x16x32_bf16 v[12:15], v[128:131], v[220:223], 0
	v_mfma_f32_16x16x32_bf16 v[8:11], v[136:139], v[220:223], 0
	v_mfma_f32_16x16x32_bf16 v[60:63], v[132:135], v[188:191], v[60:63]
	v_mfma_f32_16x16x32_bf16 v[56:59], v[140:143], v[188:191], v[56:59]
	v_mfma_f32_16x16x32_bf16 v[44:47], v[132:135], v[208:211], v[44:47]
	v_mfma_f32_16x16x32_bf16 v[40:43], v[140:143], v[208:211], v[40:43]
	v_mfma_f32_16x16x32_bf16 v[28:31], v[132:135], v[216:219], v[28:31]
	v_mfma_f32_16x16x32_bf16 v[24:27], v[140:143], v[216:219], v[24:27]
	v_mfma_f32_16x16x32_bf16 v[12:15], v[132:135], v[224:227], v[12:15]
	v_mfma_f32_16x16x32_bf16 v[8:11], v[140:143], v[224:227], v[8:11]
	s_setprio 0
	s_setprio 1
	v_mfma_f32_16x16x32_bf16 v[52:55], v[144:147], v[184:187], 0
	v_mfma_f32_16x16x32_bf16 v[48:51], v[152:155], v[184:187], 0
	v_mfma_f32_16x16x32_bf16 v[36:39], v[144:147], v[204:207], 0
	v_mfma_f32_16x16x32_bf16 v[32:35], v[152:155], v[204:207], 0
	v_mfma_f32_16x16x32_bf16 v[20:23], v[144:147], v[212:215], 0
	v_mfma_f32_16x16x32_bf16 v[16:19], v[152:155], v[212:215], 0
	v_mfma_f32_16x16x32_bf16 v[4:7], v[144:147], v[220:223], 0
	v_mfma_f32_16x16x32_bf16 v[0:3], v[152:155], v[220:223], 0
	v_mfma_f32_16x16x32_bf16 v[52:55], v[148:151], v[188:191], v[52:55]
	v_mfma_f32_16x16x32_bf16 v[48:51], v[180:183], v[188:191], v[48:51]
	v_mfma_f32_16x16x32_bf16 v[36:39], v[148:151], v[208:211], v[36:39]
	v_mfma_f32_16x16x32_bf16 v[32:35], v[180:183], v[208:211], v[32:35]
	v_mfma_f32_16x16x32_bf16 v[20:23], v[148:151], v[216:219], v[20:23]
	v_mfma_f32_16x16x32_bf16 v[16:19], v[180:183], v[216:219], v[16:19]
	v_mfma_f32_16x16x32_bf16 v[4:7], v[148:151], v[224:227], v[4:7]
	v_mfma_f32_16x16x32_bf16 v[0:3], v[180:183], v[224:227], v[0:3]
	s_setprio 0
	s_barrier
	s_add_i32 s62, 0, 0x18000
	s_add_i32 s63, 0, 0x1c000
	v_add_u32_e32 v140, s62, v201
	v_add_u32_e32 v180, s63, v201
	ds_read_b128 v[128:131], v140
	ds_read_b128 v[132:135], v140 offset:1024
	ds_read_b128 v[136:139], v140 offset:2048
	ds_read_b128 v[140:143], v140 offset:3072
	ds_read_b128 v[144:147], v180
	ds_read_b128 v[148:151], v180 offset:1024
	ds_read_b128 v[152:155], v180 offset:2048
	ds_read_b128 v[180:183], v180 offset:3072
	s_add_u32 s34, s34, s8
	s_addc_u32 s35, s35, 0
	s_mov_b32 m0, s50
	v_lshl_add_u64 v[238:239], s[34:35], 0, v[172:173]
	ds_read_b128 v[184:187], v202 offset:32768
	ds_read_b128 v[188:191], v202 offset:33792
	ds_read_b128 v[204:207], v202 offset:34816
	ds_read_b128 v[208:211], v202 offset:35840
	ds_read_b128 v[212:215], v202 offset:36864
	ds_read_b128 v[216:219], v202 offset:37888
	ds_read_b128 v[220:223], v202 offset:38912
	ds_read_b128 v[224:227], v202 offset:39936
	global_load_lds_dwordx4 v[238:239], off
	v_lshl_add_u64 v[238:239], s[34:35], 0, v[170:171]
	s_mov_b32 m0, s51
	s_nop 0
	global_load_lds_dwordx4 v[238:239], off
	s_waitcnt vmcnt(8)
	s_waitcnt lgkmcnt(0)
	s_barrier
	s_setprio 1
	s_waitcnt lgkmcnt(0)
	v_mfma_f32_16x16x32_bf16 v[124:127], v[128:131], v[184:187], v[124:127]
	v_mfma_f32_16x16x32_bf16 v[120:123], v[136:139], v[184:187], v[120:123]
	v_mfma_f32_16x16x32_bf16 v[108:111], v[128:131], v[204:207], v[108:111]
	v_mfma_f32_16x16x32_bf16 v[104:107], v[136:139], v[204:207], v[104:107]
	v_mfma_f32_16x16x32_bf16 v[92:95], v[128:131], v[212:215], v[92:95]
	v_mfma_f32_16x16x32_bf16 v[88:91], v[136:139], v[212:215], v[88:91]
	v_mfma_f32_16x16x32_bf16 v[76:79], v[128:131], v[220:223], v[76:79]
	v_mfma_f32_16x16x32_bf16 v[72:75], v[136:139], v[220:223], v[72:75]
	v_mfma_f32_16x16x32_bf16 v[124:127], v[132:135], v[188:191], v[124:127]
	v_mfma_f32_16x16x32_bf16 v[120:123], v[140:143], v[188:191], v[120:123]
	v_mfma_f32_16x16x32_bf16 v[108:111], v[132:135], v[208:211], v[108:111]
	v_mfma_f32_16x16x32_bf16 v[104:107], v[140:143], v[208:211], v[104:107]
	v_mfma_f32_16x16x32_bf16 v[92:95], v[132:135], v[216:219], v[92:95]
	v_mfma_f32_16x16x32_bf16 v[88:91], v[140:143], v[216:219], v[88:91]
	v_mfma_f32_16x16x32_bf16 v[76:79], v[132:135], v[224:227], v[76:79]
	v_mfma_f32_16x16x32_bf16 v[72:75], v[140:143], v[224:227], v[72:75]
	s_setprio 0
	s_setprio 1
	v_mfma_f32_16x16x32_bf16 v[116:119], v[144:147], v[184:187], v[116:119]
	v_mfma_f32_16x16x32_bf16 v[112:115], v[152:155], v[184:187], v[112:115]
	v_mfma_f32_16x16x32_bf16 v[100:103], v[144:147], v[204:207], v[100:103]
	v_mfma_f32_16x16x32_bf16 v[96:99], v[152:155], v[204:207], v[96:99]
	v_mfma_f32_16x16x32_bf16 v[84:87], v[144:147], v[212:215], v[84:87]
	v_mfma_f32_16x16x32_bf16 v[80:83], v[152:155], v[212:215], v[80:83]
	v_mfma_f32_16x16x32_bf16 v[68:71], v[144:147], v[220:223], v[68:71]
	v_mfma_f32_16x16x32_bf16 v[64:67], v[152:155], v[220:223], v[64:67]
	v_mfma_f32_16x16x32_bf16 v[116:119], v[148:151], v[188:191], v[116:119]
	v_mfma_f32_16x16x32_bf16 v[112:115], v[180:183], v[188:191], v[112:115]
	v_mfma_f32_16x16x32_bf16 v[100:103], v[148:151], v[208:211], v[100:103]
	v_mfma_f32_16x16x32_bf16 v[96:99], v[180:183], v[208:211], v[96:99]
	v_mfma_f32_16x16x32_bf16 v[84:87], v[148:151], v[216:219], v[84:87]
	v_mfma_f32_16x16x32_bf16 v[80:83], v[180:183], v[216:219], v[80:83]
	v_mfma_f32_16x16x32_bf16 v[68:71], v[148:151], v[224:227], v[68:71]
	v_mfma_f32_16x16x32_bf16 v[64:67], v[180:183], v[224:227], v[64:67]
	s_setprio 0
	s_barrier
	s_add_i32 s34, s62, s47
	v_lshl_add_u64 v[192:193], v[192:193], 0, s[14:15]
	s_mov_b32 m0, s34
	ds_read_b128 v[184:187], v202 offset:49152
	ds_read_b128 v[188:191], v202 offset:50176
	ds_read_b128 v[204:207], v202 offset:51200
	ds_read_b128 v[208:211], v202 offset:52224
	ds_read_b128 v[212:215], v202 offset:53248
	ds_read_b128 v[216:219], v202 offset:54272
	ds_read_b128 v[220:223], v202 offset:55296
	ds_read_b128 v[224:227], v202 offset:56320
	global_load_lds_dwordx4 v[192:193], off
	v_lshl_add_u64 v[192:193], v[228:229], 0, s[14:15]
	s_add_i32 m0, s34, 0x2000
	s_add_i32 s34, s63, s47
	global_load_lds_dwordx4 v[192:193], off
	v_lshl_add_u64 v[192:193], v[230:231], 0, s[14:15]
	s_mov_b32 m0, s34
	s_nop 0
	global_load_lds_dwordx4 v[192:193], off
	v_lshl_add_u64 v[192:193], v[232:233], 0, s[14:15]
	s_add_i32 m0, s34, 0x2000
	s_nop 0
	global_load_lds_dwordx4 v[192:193], off
	v_lshl_add_u64 v[192:193], v[234:235], 0, s[14:15]
	s_mov_b32 m0, s60
	s_nop 0
	global_load_lds_dwordx4 v[192:193], off
	v_lshl_add_u64 v[192:193], v[236:237], 0, s[14:15]
	s_mov_b32 m0, s61
	s_nop 0
	global_load_lds_dwordx4 v[192:193], off
	s_waitcnt vmcnt(8)
	s_waitcnt lgkmcnt(0)
	s_barrier
	s_setprio 1
	s_waitcnt lgkmcnt(0)
	v_mfma_f32_16x16x32_bf16 v[60:63], v[128:131], v[184:187], v[60:63]
	v_mfma_f32_16x16x32_bf16 v[56:59], v[136:139], v[184:187], v[56:59]
	v_mfma_f32_16x16x32_bf16 v[44:47], v[128:131], v[204:207], v[44:47]
	v_mfma_f32_16x16x32_bf16 v[40:43], v[136:139], v[204:207], v[40:43]
	v_mfma_f32_16x16x32_bf16 v[28:31], v[128:131], v[212:215], v[28:31]
	v_mfma_f32_16x16x32_bf16 v[24:27], v[136:139], v[212:215], v[24:27]
	v_mfma_f32_16x16x32_bf16 v[12:15], v[128:131], v[220:223], v[12:15]
	v_mfma_f32_16x16x32_bf16 v[8:11], v[136:139], v[220:223], v[8:11]
	v_mfma_f32_16x16x32_bf16 v[60:63], v[132:135], v[188:191], v[60:63]
	v_mfma_f32_16x16x32_bf16 v[56:59], v[140:143], v[188:191], v[56:59]
	v_mfma_f32_16x16x32_bf16 v[44:47], v[132:135], v[208:211], v[44:47]
	v_mfma_f32_16x16x32_bf16 v[40:43], v[140:143], v[208:211], v[40:43]
	v_mfma_f32_16x16x32_bf16 v[28:31], v[132:135], v[216:219], v[28:31]
	v_mfma_f32_16x16x32_bf16 v[24:27], v[140:143], v[216:219], v[24:27]
	v_mfma_f32_16x16x32_bf16 v[12:15], v[132:135], v[224:227], v[12:15]
	v_mfma_f32_16x16x32_bf16 v[8:11], v[140:143], v[224:227], v[8:11]
	s_setprio 0
	s_setprio 1
	v_mfma_f32_16x16x32_bf16 v[52:55], v[144:147], v[184:187], v[52:55]
	v_mfma_f32_16x16x32_bf16 v[48:51], v[152:155], v[184:187], v[48:51]
	v_mfma_f32_16x16x32_bf16 v[36:39], v[144:147], v[204:207], v[36:39]
	v_mfma_f32_16x16x32_bf16 v[32:35], v[152:155], v[204:207], v[32:35]
	v_mfma_f32_16x16x32_bf16 v[20:23], v[144:147], v[212:215], v[20:23]
	v_mfma_f32_16x16x32_bf16 v[16:19], v[152:155], v[212:215], v[16:19]
	v_mfma_f32_16x16x32_bf16 v[4:7], v[144:147], v[220:223], v[4:7]
	v_mfma_f32_16x16x32_bf16 v[0:3], v[152:155], v[220:223], v[0:3]
	v_mfma_f32_16x16x32_bf16 v[52:55], v[148:151], v[188:191], v[52:55]
	v_mfma_f32_16x16x32_bf16 v[48:51], v[180:183], v[188:191], v[48:51]
	v_mfma_f32_16x16x32_bf16 v[36:39], v[148:151], v[208:211], v[36:39]
	v_mfma_f32_16x16x32_bf16 v[32:35], v[180:183], v[208:211], v[32:35]
	v_mfma_f32_16x16x32_bf16 v[20:23], v[148:151], v[216:219], v[20:23]
	v_mfma_f32_16x16x32_bf16 v[16:19], v[180:183], v[216:219], v[16:19]
	v_mfma_f32_16x16x32_bf16 v[4:7], v[148:151], v[224:227], v[4:7]
	v_mfma_f32_16x16x32_bf16 v[0:3], v[180:183], v[224:227], v[0:3]
	s_setprio 0
	s_barrier
	s_add_u32 s2, s2, 0x100
	s_addc_u32 s3, s3, 0
	s_add_u32 s40, s40, 0x100
	s_addc_u32 s41, s41, 0
	s_mov_b32 s34, s86

.LBB0_628:
	s_ashr_i32 s13, s12, 31
	s_lshl_b64 s[6:7], s[12:13], 19
	s_add_u32 s6, s30, s6
	s_addc_u32 s7, s31, s7
	s_and_b64 s[24:25], s[38:39], exec
	s_cselect_b32 s13, s7, s35
	s_cselect_b32 s29, s6, s34
	s_ashr_i32 s5, s4, 31
	s_lshl_b64 s[24:25], s[4:5], 19
	s_add_u32 s24, s49, s24
	s_addc_u32 s25, s50, s25
	s_and_b64 s[42:43], s[38:39], exec
	s_cselect_b32 s5, s25, s41
	s_cselect_b32 s82, s24, s40
	s_add_u32 s34, s34, 0x40080
	s_addc_u32 s35, s35, 0
	s_add_u32 s83, s40, 0x100
	s_addc_u32 s84, s41, 0
	s_mov_b32 s85, -2
	s_add_u32 s40, s34, 0xfffc0080
	s_addc_u32 s41, s35, -1
	s_add_i32 s62, 0, 0x10000
	s_cmp_eq_u32 s85, 12
	s_cselect_b32 s43, s13, s41
	s_cselect_b32 s42, s29, s40
	s_cselect_b32 s41, s5, s84
	s_cselect_b32 s40, s82, s83
	s_add_i32 s63, 0, 0x14000
	s_add_u32 s86, s34, 0xfffc0000
	s_addc_u32 s87, s35, -1
	s_mov_b32 m0, s76
	v_add_u32_e32 v152, s62, v172
	v_add_u32_e32 v158, s63, v172
	v_add_u32_e32 v245, s62, v243
	v_add_u32_e32 v246, s63, v243
	global_load_lds_dwordx4 v132, s[86:87]
	s_mov_b32 m0, s77
	ds_read_b128 v[128:131], v152
	global_load_lds_dwordx4 v136, s[86:87]
	ds_read_b128 v[144:147], v245
	ds_read_b128 v[148:151], v152 offset:2048
	ds_read_b128 v[152:155], v245 offset:2048
	ds_read_b128 v[174:177], v158
	ds_read_b128 v[178:181], v246
	ds_read_b128 v[182:185], v158 offset:2048
	ds_read_b128 v[186:189], v246 offset:2048
	ds_read_b128 v[190:193], v173
	ds_read_b128 v[198:201], v244
	ds_read_b128 v[202:205], v173 offset:2048
	ds_read_b128 v[206:209], v244 offset:2048
	ds_read_b128 v[210:213], v173 offset:4096
	ds_read_b128 v[214:217], v244 offset:4096
	ds_read_b128 v[218:221], v173 offset:6144
	ds_read_b128 v[222:225], v244 offset:6144
	s_waitcnt vmcnt(6)
	s_waitcnt lgkmcnt(0)
	s_barrier
	s_setprio 1
	s_waitcnt lgkmcnt(0)
	v_mfma_f32_16x16x32_bf16 v[124:127], v[128:131], v[190:193], 0
	v_mfma_f32_16x16x32_bf16 v[116:119], v[148:151], v[190:193], 0
	v_mfma_f32_16x16x32_bf16 v[108:111], v[128:131], v[202:205], 0
	s_add_i32 m0, s51, 0xc000
	v_mfma_f32_16x16x32_bf16 v[100:103], v[148:151], v[202:205], 0
	v_mfma_f32_16x16x32_bf16 v[92:95], v[128:131], v[210:213], 0
	global_load_lds_dwordx4 v132, s[34:35]
	v_mfma_f32_16x16x32_bf16 v[84:87], v[148:151], v[210:213], 0
	v_mfma_f32_16x16x32_bf16 v[76:79], v[128:131], v[218:221], 0
	v_mfma_f32_16x16x32_bf16 v[68:71], v[148:151], v[218:221], 0
	v_mfma_f32_16x16x32_bf16 v[124:127], v[144:147], v[198:201], v[124:127]
	v_mfma_f32_16x16x32_bf16 v[116:119], v[152:155], v[198:201], v[116:119]
	v_mfma_f32_16x16x32_bf16 v[108:111], v[144:147], v[206:209], v[108:111]
	s_add_i32 m0, s51, 0xe000
	v_mfma_f32_16x16x32_bf16 v[100:103], v[152:155], v[206:209], v[100:103]
	v_mfma_f32_16x16x32_bf16 v[92:95], v[144:147], v[214:217], v[92:95]
	global_load_lds_dwordx4 v136, s[34:35]
	v_mfma_f32_16x16x32_bf16 v[84:87], v[152:155], v[214:217], v[84:87]
	v_mfma_f32_16x16x32_bf16 v[76:79], v[144:147], v[222:225], v[76:79]
	v_mfma_f32_16x16x32_bf16 v[68:71], v[152:155], v[222:225], v[68:71]
	s_setprio 0
	s_setprio 1
	v_mfma_f32_16x16x32_bf16 v[120:123], v[174:177], v[190:193], 0
	v_mfma_f32_16x16x32_bf16 v[112:115], v[182:185], v[190:193], 0
	v_mfma_f32_16x16x32_bf16 v[104:107], v[174:177], v[202:205], 0
	v_mfma_f32_16x16x32_bf16 v[96:99], v[182:185], v[202:205], 0
	v_mfma_f32_16x16x32_bf16 v[88:91], v[174:177], v[210:213], 0
	v_mfma_f32_16x16x32_bf16 v[80:83], v[182:185], v[210:213], 0
	v_mfma_f32_16x16x32_bf16 v[72:75], v[174:177], v[218:221], 0
	v_mfma_f32_16x16x32_bf16 v[64:67], v[182:185], v[218:221], 0
	v_mfma_f32_16x16x32_bf16 v[120:123], v[178:181], v[198:201], v[120:123]
	v_mfma_f32_16x16x32_bf16 v[112:115], v[186:189], v[198:201], v[112:115]
	v_mfma_f32_16x16x32_bf16 v[104:107], v[178:181], v[206:209], v[104:107]
	v_mfma_f32_16x16x32_bf16 v[96:99], v[186:189], v[206:209], v[96:99]
	v_mfma_f32_16x16x32_bf16 v[88:91], v[178:181], v[214:217], v[88:91]
	v_mfma_f32_16x16x32_bf16 v[80:83], v[186:189], v[214:217], v[80:83]
	v_mfma_f32_16x16x32_bf16 v[72:75], v[178:181], v[222:225], v[72:75]
	v_mfma_f32_16x16x32_bf16 v[64:67], v[186:189], v[222:225], v[64:67]
	s_setprio 0
	s_barrier
	s_add_i32 s62, s62, s48
	s_mov_b32 m0, s62
	ds_read_b128 v[190:193], v173 offset:16384
	global_load_lds_dwordx4 v134, s[40:41]
	s_add_i32 m0, s62, 0x2000
	ds_read_b128 v[198:201], v244 offset:16384
	global_load_lds_dwordx4 v138, s[40:41]
	ds_read_b128 v[202:205], v173 offset:18432
	ds_read_b128 v[206:209], v244 offset:18432
	ds_read_b128 v[210:213], v173 offset:20480
	ds_read_b128 v[214:217], v244 offset:20480
	ds_read_b128 v[218:221], v173 offset:22528
	ds_read_b128 v[222:225], v244 offset:22528
	s_add_u32 s86, s40, 0x40000
	s_addc_u32 s87, s41, 0
	s_add_i32 s62, s63, s48
	s_waitcnt vmcnt(4)
	s_waitcnt lgkmcnt(0)
	s_barrier
	s_setprio 1
	s_waitcnt lgkmcnt(0)
	v_mfma_f32_16x16x32_bf16 v[60:63], v[128:131], v[190:193], 0
	v_mfma_f32_16x16x32_bf16 v[52:55], v[148:151], v[190:193], 0
	v_mfma_f32_16x16x32_bf16 v[44:47], v[128:131], v[202:205], 0
	s_mov_b32 m0, s62
	v_mfma_f32_16x16x32_bf16 v[36:39], v[148:151], v[202:205], 0
	v_mfma_f32_16x16x32_bf16 v[28:31], v[128:131], v[210:213], 0
	global_load_lds_dwordx4 v134, s[86:87]
	v_mfma_f32_16x16x32_bf16 v[20:23], v[148:151], v[210:213], 0
	v_mfma_f32_16x16x32_bf16 v[8:11], v[128:131], v[218:221], 0
	v_mfma_f32_16x16x32_bf16 v[4:7], v[148:151], v[218:221], 0
	v_mfma_f32_16x16x32_bf16 v[60:63], v[144:147], v[198:201], v[60:63]
	v_mfma_f32_16x16x32_bf16 v[52:55], v[152:155], v[198:201], v[52:55]
	v_mfma_f32_16x16x32_bf16 v[44:47], v[144:147], v[206:209], v[44:47]
	s_add_i32 m0, s62, 0x2000
	v_mfma_f32_16x16x32_bf16 v[36:39], v[152:155], v[206:209], v[36:39]
	v_mfma_f32_16x16x32_bf16 v[28:31], v[144:147], v[214:217], v[28:31]
	global_load_lds_dwordx4 v138, s[86:87]
	v_mfma_f32_16x16x32_bf16 v[20:23], v[152:155], v[214:217], v[20:23]
	v_mfma_f32_16x16x32_bf16 v[8:11], v[144:147], v[222:225], v[8:11]
	v_mfma_f32_16x16x32_bf16 v[4:7], v[152:155], v[222:225], v[4:7]
	s_setprio 0
	s_setprio 1
	v_mfma_f32_16x16x32_bf16 v[56:59], v[174:177], v[190:193], 0
	v_mfma_f32_16x16x32_bf16 v[48:51], v[182:185], v[190:193], 0
	v_mfma_f32_16x16x32_bf16 v[40:43], v[174:177], v[202:205], 0
	v_mfma_f32_16x16x32_bf16 v[32:35], v[182:185], v[202:205], 0
	v_mfma_f32_16x16x32_bf16 v[24:27], v[174:177], v[210:213], 0
	v_mfma_f32_16x16x32_bf16 v[16:19], v[182:185], v[210:213], 0
	v_mfma_f32_16x16x32_bf16 v[12:15], v[174:177], v[218:221], 0
	v_mfma_f32_16x16x32_bf16 v[0:3], v[182:185], v[218:221], 0
	v_mfma_f32_16x16x32_bf16 v[56:59], v[178:181], v[198:201], v[56:59]
	v_mfma_f32_16x16x32_bf16 v[48:51], v[186:189], v[198:201], v[48:51]
	v_mfma_f32_16x16x32_bf16 v[40:43], v[178:181], v[206:209], v[40:43]
	v_mfma_f32_16x16x32_bf16 v[32:35], v[186:189], v[206:209], v[32:35]
	v_mfma_f32_16x16x32_bf16 v[24:27], v[178:181], v[214:217], v[24:27]
	v_mfma_f32_16x16x32_bf16 v[16:19], v[186:189], v[214:217], v[16:19]
	v_mfma_f32_16x16x32_bf16 v[12:15], v[178:181], v[222:225], v[12:15]
	v_mfma_f32_16x16x32_bf16 v[0:3], v[186:189], v[222:225], v[0:3]
	s_setprio 0
	s_barrier
	s_add_i32 s62, 0, 0x18000
	s_add_i32 s63, 0, 0x1c000
	s_mov_b32 m0, s51
	v_add_u32_e32 v152, s62, v172
	v_add_u32_e32 v158, s63, v172
	v_add_u32_e32 v245, s62, v243
	v_add_u32_e32 v246, s63, v243
	global_load_lds_dwordx4 v132, s[42:43]
	s_mov_b32 m0, s60
	ds_read_b128 v[128:131], v152
	global_load_lds_dwordx4 v136, s[42:43]
	ds_read_b128 v[144:147], v245
	ds_read_b128 v[148:151], v152 offset:2048
	ds_read_b128 v[152:155], v245 offset:2048
	ds_read_b128 v[174:177], v158
	ds_read_b128 v[178:181], v246
	ds_read_b128 v[182:185], v158 offset:2048
	ds_read_b128 v[186:189], v246 offset:2048
	ds_read_b128 v[190:193], v173 offset:32768
	ds_read_b128 v[198:201], v244 offset:32768
	ds_read_b128 v[202:205], v173 offset:34816
	ds_read_b128 v[206:209], v244 offset:34816
	ds_read_b128 v[210:213], v173 offset:36864
	ds_read_b128 v[214:217], v244 offset:36864
	ds_read_b128 v[218:221], v173 offset:38912
	ds_read_b128 v[222:225], v244 offset:38912
	s_add_u32 s42, s42, 0x40000
	s_addc_u32 s43, s43, 0
	s_waitcnt vmcnt(6)
	s_waitcnt lgkmcnt(0)
	s_barrier
	s_setprio 1
	s_waitcnt lgkmcnt(0)
	v_mfma_f32_16x16x32_bf16 v[124:127], v[128:131], v[190:193], v[124:127]
	v_mfma_f32_16x16x32_bf16 v[116:119], v[148:151], v[190:193], v[116:119]
	v_mfma_f32_16x16x32_bf16 v[108:111], v[128:131], v[202:205], v[108:111]
	s_mov_b32 m0, s61
	v_mfma_f32_16x16x32_bf16 v[100:103], v[148:151], v[202:205], v[100:103]
	v_mfma_f32_16x16x32_bf16 v[92:95], v[128:131], v[210:213], v[92:95]
	global_load_lds_dwordx4 v132, s[42:43]
	v_mfma_f32_16x16x32_bf16 v[84:87], v[148:151], v[210:213], v[84:87]
	v_mfma_f32_16x16x32_bf16 v[76:79], v[128:131], v[218:221], v[76:79]
	v_mfma_f32_16x16x32_bf16 v[68:71], v[148:151], v[218:221], v[68:71]
	v_mfma_f32_16x16x32_bf16 v[124:127], v[144:147], v[198:201], v[124:127]
	v_mfma_f32_16x16x32_bf16 v[116:119], v[152:155], v[198:201], v[116:119]
	v_mfma_f32_16x16x32_bf16 v[108:111], v[144:147], v[206:209], v[108:111]
	s_mov_b32 m0, s64
	v_mfma_f32_16x16x32_bf16 v[100:103], v[152:155], v[206:209], v[100:103]
	v_mfma_f32_16x16x32_bf16 v[92:95], v[144:147], v[214:217], v[92:95]
	global_load_lds_dwordx4 v136, s[42:43]
	v_mfma_f32_16x16x32_bf16 v[84:87], v[152:155], v[214:217], v[84:87]
	v_mfma_f32_16x16x32_bf16 v[76:79], v[144:147], v[222:225], v[76:79]
	v_mfma_f32_16x16x32_bf16 v[68:71], v[152:155], v[222:225], v[68:71]
	s_setprio 0
	s_setprio 1
	v_mfma_f32_16x16x32_bf16 v[120:123], v[174:177], v[190:193], v[120:123]
	v_mfma_f32_16x16x32_bf16 v[112:115], v[182:185], v[190:193], v[112:115]
	v_mfma_f32_16x16x32_bf16 v[104:107], v[174:177], v[202:205], v[104:107]
	v_mfma_f32_16x16x32_bf16 v[96:99], v[182:185], v[202:205], v[96:99]
	v_mfma_f32_16x16x32_bf16 v[88:91], v[174:177], v[210:213], v[88:91]
	v_mfma_f32_16x16x32_bf16 v[80:83], v[182:185], v[210:213], v[80:83]
	v_mfma_f32_16x16x32_bf16 v[72:75], v[174:177], v[218:221], v[72:75]
	v_mfma_f32_16x16x32_bf16 v[64:67], v[182:185], v[218:221], v[64:67]
	v_mfma_f32_16x16x32_bf16 v[120:123], v[178:181], v[198:201], v[120:123]
	v_mfma_f32_16x16x32_bf16 v[112:115], v[186:189], v[198:201], v[112:115]
	v_mfma_f32_16x16x32_bf16 v[104:107], v[178:181], v[206:209], v[104:107]
	v_mfma_f32_16x16x32_bf16 v[96:99], v[186:189], v[206:209], v[96:99]
	v_mfma_f32_16x16x32_bf16 v[88:91], v[178:181], v[214:217], v[88:91]
	v_mfma_f32_16x16x32_bf16 v[80:83], v[186:189], v[214:217], v[80:83]
	v_mfma_f32_16x16x32_bf16 v[72:75], v[178:181], v[222:225], v[72:75]
	v_mfma_f32_16x16x32_bf16 v[64:67], v[186:189], v[222:225], v[64:67]
	s_setprio 0
	s_barrier
	s_add_i32 s42, s62, s48
	s_add_u32 s40, s40, 0x80
	s_addc_u32 s41, s41, 0
	s_mov_b32 m0, s42
	ds_read_b128 v[190:193], v173 offset:49152
	global_load_lds_dwordx4 v134, s[40:41]
	s_add_i32 m0, s42, 0x2000
	ds_read_b128 v[198:201], v244 offset:49152
	global_load_lds_dwordx4 v138, s[40:41]
	ds_read_b128 v[202:205], v173 offset:51200
	ds_read_b128 v[206:209], v244 offset:51200
	ds_read_b128 v[210:213], v173 offset:53248
	ds_read_b128 v[214:217], v244 offset:53248
	ds_read_b128 v[218:221], v173 offset:55296
	ds_read_b128 v[222:225], v244 offset:55296
	s_add_u32 s40, s40, 0x40000
	s_addc_u32 s41, s41, 0
	s_add_i32 s42, s63, s48
	s_waitcnt vmcnt(4)
	s_waitcnt lgkmcnt(0)
	s_barrier
	s_setprio 1
	s_waitcnt lgkmcnt(0)
	v_mfma_f32_16x16x32_bf16 v[60:63], v[128:131], v[190:193], v[60:63]
	v_mfma_f32_16x16x32_bf16 v[52:55], v[148:151], v[190:193], v[52:55]
	v_mfma_f32_16x16x32_bf16 v[44:47], v[128:131], v[202:205], v[44:47]
	s_mov_b32 m0, s42
	v_mfma_f32_16x16x32_bf16 v[36:39], v[148:151], v[202:205], v[36:39]
	v_mfma_f32_16x16x32_bf16 v[28:31], v[128:131], v[210:213], v[28:31]
	global_load_lds_dwordx4 v134, s[40:41]
	v_mfma_f32_16x16x32_bf16 v[20:23], v[148:151], v[210:213], v[20:23]
	v_mfma_f32_16x16x32_bf16 v[8:11], v[128:131], v[218:221], v[8:11]
	v_mfma_f32_16x16x32_bf16 v[4:7], v[148:151], v[218:221], v[4:7]
	v_mfma_f32_16x16x32_bf16 v[60:63], v[144:147], v[198:201], v[60:63]
	v_mfma_f32_16x16x32_bf16 v[52:55], v[152:155], v[198:201], v[52:55]
	v_mfma_f32_16x16x32_bf16 v[44:47], v[144:147], v[206:209], v[44:47]
	s_add_i32 m0, s42, 0x2000
	v_mfma_f32_16x16x32_bf16 v[36:39], v[152:155], v[206:209], v[36:39]
	v_mfma_f32_16x16x32_bf16 v[28:31], v[144:147], v[214:217], v[28:31]
	global_load_lds_dwordx4 v138, s[40:41]
	v_mfma_f32_16x16x32_bf16 v[20:23], v[152:155], v[214:217], v[20:23]
	v_mfma_f32_16x16x32_bf16 v[8:11], v[144:147], v[222:225], v[8:11]
	v_mfma_f32_16x16x32_bf16 v[4:7], v[152:155], v[222:225], v[4:7]
	s_setprio 0
	s_setprio 1
	v_mfma_f32_16x16x32_bf16 v[56:59], v[174:177], v[190:193], v[56:59]
	v_mfma_f32_16x16x32_bf16 v[48:51], v[182:185], v[190:193], v[48:51]
	v_mfma_f32_16x16x32_bf16 v[40:43], v[174:177], v[202:205], v[40:43]
	v_mfma_f32_16x16x32_bf16 v[32:35], v[182:185], v[202:205], v[32:35]
	v_mfma_f32_16x16x32_bf16 v[24:27], v[174:177], v[210:213], v[24:27]
	v_mfma_f32_16x16x32_bf16 v[16:19], v[182:185], v[210:213], v[16:19]
	v_mfma_f32_16x16x32_bf16 v[12:15], v[174:177], v[218:221], v[12:15]
	v_mfma_f32_16x16x32_bf16 v[0:3], v[182:185], v[218:221], v[0:3]
	v_mfma_f32_16x16x32_bf16 v[56:59], v[178:181], v[198:201], v[56:59]
	v_mfma_f32_16x16x32_bf16 v[48:51], v[186:189], v[198:201], v[48:51]
	v_mfma_f32_16x16x32_bf16 v[40:43], v[178:181], v[206:209], v[40:43]
	v_mfma_f32_16x16x32_bf16 v[32:35], v[186:189], v[206:209], v[32:35]
	v_mfma_f32_16x16x32_bf16 v[24:27], v[178:181], v[214:217], v[24:27]
	v_mfma_f32_16x16x32_bf16 v[16:19], v[186:189], v[214:217], v[16:19]
	v_mfma_f32_16x16x32_bf16 v[12:15], v[178:181], v[222:225], v[12:15]
	v_mfma_f32_16x16x32_bf16 v[0:3], v[186:189], v[222:225], v[0:3]
	s_setprio 0
	s_barrier
	s_add_i32 s85, s85, 2
	s_add_u32 s34, s34, 0x100
	s_addc_u32 s35, s35, 0
	s_add_u32 s83, s83, 0x100
	s_addc_u32 s84, s84, 0
